# t1 + in-proj rstd prefetch + attention epilogue gate-load hoist + all waves' stores drained before the P1-end publish (every workgroup still writes back L2)
# baseline (speedup 1.0000x reference)
.LBB0_317:
	s_cmp_gt_i32 s71, 2
	s_cselect_b64 s[0:1], -1, 0
	s_and_b64 s[2:3], s[34:35], s[0:1]
	s_andn2_b64 vcc, exec, s[2:3]
	s_cbranch_vccnz .LBB0_371
	s_waitcnt vmcnt(0)
	s_barrier
	v_cmp_eq_u32_e32 vcc, 0, v161
	s_and_saveexec_b64 s[2:3], vcc
	s_cbranch_execz .Lsyn_pub_done
	buffer_wbl2 sc1
	s_waitcnt vmcnt(0)
	v_mov_b32_e32 v0, 0x3900
	v_mov_b32_e32 v1, 1
	global_atomic_add v0, v1, s[72:73]
